# in-proj first tile: weight-conversion records fetched in parallel with the H-row records (one round trip instead of two)
# speedup vs baseline: 1.0055x; 1.0022x over previous
.Lip_block:
	s_cmp_lg_u32 s66, 0
	s_cbranch_scc1 .Lip_noconvpf
	s_add_u32 s46, s94, 0xcbcd000
	s_addc_u32 s47, s95, 0
	v_and_b32_e32 v67, 63, v137
	v_lshlrev_b32_e32 v67, 4, v67
	global_load_dwordx4 v[72:75], v67, s[46:47] sc1

.Lip_ok:
	s_cmp_lg_u32 s66, 0
	s_cbranch_scc1 .Lip_nodep
	s_add_i32 s64, s64, 0x1000
	v_cmp_ne_u32_e32 vcc, s64, v72
	s_cbranch_vccz .Lip_cok
	s_add_u32 s46, s94, 0xcbcd000
	s_addc_u32 s47, s95, 0
	v_and_b32_e32 v66, 63, v137
	v_lshlrev_b32_e32 v66, 4, v66
	s_mov_b32 s65, 0x100000
